# retention loop: silu(g) prefetched 1 chunk ahead and q/k/v 2 chunks ahead (parity-selected register sets); wait counts re-derived
# baseline (speedup 1.0000x reference)
; #define LAS __attribute__((address_space(3)))
; #define LBAR() do { asm volatile("s_waitcnt lgkmcnt(0)" ::: "memory"); __builtin_amdgcn_s_barrier(); asm volatile("" ::: "memory"); } while (0)
; template <int WIN>
; __device__ __forceinline__ void pool_block_t(LAS unsigned char* lds, const Ptrs& P, int g, int tile0, int tstep, int tid) {
;     ...
;     POOL_LOAD(tile0);
;     for (int tile = tile0; tile < M / 64; tile += tstep) {
; #pragma unroll
;         for (int k = 0; k < 3; ++k) { const int idx = tid + 512 * k; if (idx < 79 * 16) *(LAS v4u*)(Us + (idx >> 4) * S136 + vseg * 8) = pf[k]; }
;         LBAR();
;         if (tile + tstep < M / 64) POOL_LOAD(tile + tstep);
.LBB0_539:
	s_waitcnt vmcnt(0)
	ds_write_b128 v185, v[16:19]
	s_and_saveexec_b64 s[56:57], s[4:5]
	ds_write_b128 v85, v[24:27]
	s_or_b64 exec, exec, s[56:57]
	s_and_saveexec_b64 s[56:57], s[6:7]
	ds_write_b128 v132, v[20:23]
	s_or_b64 exec, exec, s[56:57]
	s_waitcnt lgkmcnt(0)
	s_barrier
	s_add_i32 s70, s70, s68
	s_cmpk_gt_u32 s70, 0x3ff
	s_cselect_b64 s[56:57], -1, 0
	s_cmpk_lt_u32 s70, 0x400
	s_mov_b64 s[62:63], -1
	s_cbranch_scc1 .LBB0_545
	s_add_i32 s71, s72, s13
	s_mov_b64 s[62:63], 0

; #define LAS __attribute__((address_space(3)))
; #define LBAR() do { asm volatile("s_waitcnt lgkmcnt(0)" ::: "memory"); __builtin_amdgcn_s_barrier(); asm volatile("" ::: "memory"); } while (0)
; template <int WIN>
; __device__ __forceinline__ void pool_block_t(LAS unsigned char* lds, const Ptrs& P, int g, int tile0, int tstep, int tid) {
;     ...
;     POOL_LOAD(tile0);
;     for (int tile = tile0; tile < M / 64; tile += tstep) {
; #pragma unroll
;         for (int k = 0; k < 3; ++k) { const int idx = tid + 512 * k; if (idx < 79 * 16) *(LAS v4u*)(Us + (idx >> 4) * S136 + vseg * 8) = pf[k]; }
;         LBAR();
;         if (tile + tstep < M / 64) POOL_LOAD(tile + tstep);
.LBB0_564:
	s_waitcnt vmcnt(0)
	ds_write_b128 v185, v[16:19]
	s_and_saveexec_b64 s[56:57], s[4:5]
	ds_write_b128 v30, v[24:27]
	s_or_b64 exec, exec, s[56:57]
	s_and_saveexec_b64 s[56:57], s[6:7]
	ds_write_b128 v31, v[20:23]
	s_or_b64 exec, exec, s[56:57]
	s_waitcnt lgkmcnt(0)
	s_barrier
	s_add_i32 s70, s70, s68
	s_cmpk_gt_u32 s70, 0x3ff
	s_cselect_b64 s[56:57], -1, 0
	s_cmpk_lt_u32 s70, 0x400
	s_mov_b64 s[62:63], -1
	s_cbranch_scc1 .LBB0_570
	s_add_i32 s71, s72, s13
	s_mov_b64 s[62:63], 0

; #define LAS __attribute__((address_space(3)))
; #define LBAR() do { asm volatile("s_waitcnt lgkmcnt(0)" ::: "memory"); __builtin_amdgcn_s_barrier(); asm volatile("" ::: "memory"); } while (0)
; template <int WIN>
; __device__ __forceinline__ void pool_block_t(LAS unsigned char* lds, const Ptrs& P, int g, int tile0, int tstep, int tid) {
;     ...
;     POOL_LOAD(tile0);
;     for (int tile = tile0; tile < M / 64; tile += tstep) {
; #pragma unroll
;         for (int k = 0; k < 3; ++k) { const int idx = tid + 512 * k; if (idx < 79 * 16) *(LAS v4u*)(Us + (idx >> 4) * S136 + vseg * 8) = pf[k]; }
;         LBAR();
;         if (tile + tstep < M / 64) POOL_LOAD(tile + tstep);
.LBB0_591:
	s_waitcnt vmcnt(0)
	ds_write_b128 v185, v[16:19]
	s_and_saveexec_b64 s[56:57], s[4:5]
	ds_write_b128 v30, v[24:27]
	s_or_b64 exec, exec, s[56:57]
	s_and_saveexec_b64 s[56:57], s[6:7]
	ds_write_b128 v31, v[20:23]
	s_or_b64 exec, exec, s[56:57]
	s_waitcnt lgkmcnt(0)
	s_barrier
	s_add_i32 s69, s69, s68
	s_cmpk_gt_u32 s69, 0x3ff
	s_cselect_b64 s[56:57], -1, 0
	s_cmpk_lt_u32 s69, 0x400
	s_mov_b64 s[62:63], -1
	s_cbranch_scc1 .LBB0_597
	s_add_i32 s70, s71, s13
	s_mov_b64 s[62:63], 0

; #define LAS __attribute__((address_space(3)))
; #define LBAR() do { asm volatile("s_waitcnt lgkmcnt(0)" ::: "memory"); __builtin_amdgcn_s_barrier(); asm volatile("" ::: "memory"); } while (0)
; template <int WIN>
; __device__ __forceinline__ void pool_block_t(LAS unsigned char* lds, const Ptrs& P, int g, int tile0, int tstep, int tid) {
;     ...
;     POOL_LOAD(tile0);
;     for (int tile = tile0; tile < M / 64; tile += tstep) {
; #pragma unroll
;         for (int k = 0; k < 3; ++k) { const int idx = tid + 512 * k; if (idx < 79 * 16) *(LAS v4u*)(Us + (idx >> 4) * S136 + vseg * 8) = pf[k]; }
;         LBAR();
;         if (tile + tstep < M / 64) POOL_LOAD(tile + tstep);
.LBB0_616:
	s_waitcnt vmcnt(0)
	ds_write_b128 v185, v[16:19]
	s_and_saveexec_b64 s[18:19], s[4:5]
	ds_write_b128 v30, v[24:27]
	s_or_b64 exec, exec, s[18:19]
	s_and_saveexec_b64 s[18:19], s[6:7]
	ds_write_b128 v31, v[20:23]
	s_or_b64 exec, exec, s[18:19]
	s_waitcnt lgkmcnt(0)
	s_barrier
	s_add_i32 s12, s12, s68
	s_cmpk_gt_u32 s12, 0x3ff
	s_cselect_b64 s[18:19], -1, 0
	s_cmpk_lt_u32 s12, 0x400
	s_mov_b64 s[20:21], -1
	s_cbranch_scc1 .LBB0_622
	s_add_i32 s62, s63, s13
	s_mov_b64 s[20:21], 0

; #define LAS __attribute__((address_space(3)))
; __device__ __forceinline__ void retention_unit(LAS unsigned char* lds, const Ptrs& P, int b, int h, int tid) {
;     ...
;     for (int i = tid; i < 128 * S72 * 2 / 16; i += NTHREADS) ((LAS v4u*)St)[i] = (v4u){0u, 0u, 0u, 0u};
;     f32x4 st[4];
; #pragma unroll
;     for (int i = 0; i < 4; ++i) st[i] = (f32x4){0.f, 0.f, 0.f, 0.f};
;     const int lrow = tid >> 3, lseg = tid & 7, vrow0 = tid >> 4, vseg = tid & 15;
;     const size_t tok0 = (size_t)b * SEQ;
;     const bf16* gq = P.Q + (tok0 + lrow) * 256 + h * 64 + lseg * 8; const bf16* gk = P.K + (tok0 + lrow) * 256 + h * 64 + lseg * 8;
;     const bf16* gv = P.V + (tok0 + vrow0) * 512 + h * 128 + vseg * 8;
;     const bf16* gsl = P.SG + (tok0 + fr) * 512 + h * 128 + 16 * w + 4 * fq;
;     bf16* gol = P.RS + (tok0 + fr) * 1024 + h * 128 + 16 * w + 4 * fq;
;     v4u rq = __builtin_nontemporal_load((const v4u*)gq), rk = __builtin_nontemporal_load((const v4u*)gk), rv0 = __builtin_nontemporal_load((const v4u*)gv), rv1 = __builtin_nontemporal_load((const v4u*)(gv + 32 * 512));
;     const float dkey = ex2((float)(63 - lrow) * lg), dch = ex2(64.f * lg);
;     const f32x4 gng4 = *(const f32x4*)(P.gng + h * 128 + 16 * w + 4 * fq);
;     const int it3 = w >> 1;
;     float dqv[4]; f32x4 decv[2];
; #pragma unroll
;     for (int it = 0; it < 4; ++it) dqv[it] = ex2((float)(16 * it + fr + 1) * lg);
; #pragma unroll
;     for (int j2 = 0; j2 < 2; ++j2)
; #pragma unroll
;         for (int r = 0; r < 4; ++r) decv[j2][r] = ex2(__builtin_fabsf((float)((16 * it3 + fr) - (16 * ((w & 1) * 2 + j2) + 4 * fq + r))) * lg);
;     f32x4 op[4]; v2u sgr[4];
; #pragma unroll
;     for (int it = 0; it < 4; ++it) { op[it] = (f32x4){0.f, 0.f, 0.f, 0.f}; sgr[it] = (v2u){0u, 0u}; }
;     for (int n = 0; n <= 32; ++n) {
;         LAS unsigned char* bufc = lds + (n & 1) * RSET;
;         LAS bf16* Qs = (LAS bf16*)(bufc + ROFF_Q); LAS bf16* Ks = (LAS bf16*)(bufc + ROFF_K); LAS bf16* K2s = (LAS bf16*)(bufc + ROFF_K2); LAS bf16* Vs = (LAS bf16*)(bufc + ROFF_V);
;         if (n < 32) {
;             *(LAS v4u*)(Qs + lrow * S72 + lseg * 8) = rq; *(LAS v4u*)(Ks + lrow * S72 + lseg * 8) = rk;
;             v4u k2;
; #pragma unroll
;             for (int t = 0; t < 4; ++t) k2[t] = pk2(bflo(rk[t]) * dkey, bfhi(rk[t]) * dkey);
;             *(LAS v4u*)(K2s + lrow * S72 + lseg * 8) = k2;
.LBB0_655:
	v_add_u32_e32 v1, 0x200, v1
	v_cmp_lt_u32_e32 vcc, s7, v1
	ds_write_b128 v0, v[180:183]
	s_or_b64 s[16:17], vcc, s[16:17]
	v_add_u32_e32 v0, 0x2000, v0
	s_andn2_b64 exec, exec, s[16:17]
	s_cbranch_execnz .LBB0_655
	s_or_b64 exec, exec, s[16:17]
	s_ashr_i32 s18, s86, 2
	s_ashr_i32 s19, s18, 31
	s_lshl_b64 s[16:17], s[18:19], 11
	v_mov_b32_e32 v1, s17
	v_or_b32_e32 v0, s16, v145
	v_lshlrev_b64 v[0:1], 9, v[0:1]
	v_lshl_add_u64 v[2:3], s[36:37], 0, v[0:1]
	s_lshl_b32 s4, s88, 7
	v_lshl_add_u64 v[0:1], s[48:49], 0, v[0:1]
	v_lshl_add_u64 v[2:3], v[2:3], 0, s[4:5]
	v_lshl_add_u64 v[0:1], v[0:1], 0, s[4:5]
	s_waitcnt vmcnt(2)
	v_lshl_add_u64 v[6:7], v[2:3], 0, v[72:73]
	v_lshl_add_u64 v[4:5], v[0:1], 0, v[72:73]
	v_mov_b32_e32 v1, s17
	v_or_b32_e32 v0, s16, v80
	global_load_dwordx4 v[8:11], v[6:7], off nt
	global_load_dwordx4 v[12:15], v[4:5], off nt
	v_lshlrev_b64 v[0:1], 10, v[0:1]
	s_lshl_b32 s90, s88, 8
	s_mov_b32 s91, s5
	v_lshl_add_u64 v[0:1], s[42:43], 0, v[0:1]
	v_lshl_add_u64 v[0:1], v[0:1], 0, s[90:91]
	v_lshl_add_u64 v[28:29], v[0:1], 0, v[84:85]
	v_add_co_u32_e32 v0, vcc, s21, v28
	s_and_b32 s93, s85, 3
	s_nop 0
	v_addc_co_u32_e32 v1, vcc, 0, v29, vcc
	global_load_dwordx4 v[16:19], v[28:29], off nt
	global_load_dwordx4 v[20:23], v[0:1], off nt
	s_lshr_b32 s87, s92, 6
	s_waitcnt lgkmcnt(0)
	v_mul_f32_e32 v0, s89, v147
	s_lshl_b32 s94, s88, 9
	s_lshl_b32 s91, s93, 7
	s_lshl_b32 s90, s93, 8
	s_lshl_b32 s88, s87, 4
	v_exp_f32_e32 v102, v0
	s_add_u32 s93, s50, s94
	s_addc_u32 s95, s51, 0
	s_and_b32 s94, s92, 0xffffffc0
	s_add_u32 s94, s93, s94
	s_addc_u32 s95, s95, 0
	global_load_dwordx4 v[0:3], v127, s[94:95]
	v_mov_b32_e32 v103, v102
	s_lshr_b32 s93, s92, 3
	s_lshr_b32 s92, s92, 5
	s_and_b32 s93, s93, 0x1ffffff0
	s_and_b32 s92, s92, 2
	s_waitcnt vmcnt(5)
	v_or_b32_e32 v24, s93, v144
	s_lshl_b32 s93, s92, 4
	v_or_b32_e32 v60, s93, v144
	v_mul_lo_u32 v62, v24, s20
	v_add_u32_e32 v176, v166, v62
	v_or_b32_e32 v25, s93, v146
	v_add_u32_e32 v26, v24, v152
	v_add_u32_e32 v27, v24, v153
	v_add_u32_e32 v30, v24, v154
	v_sub_u32_e32 v31, v24, v146
	v_sub_u32_e32 v24, v24, v25
	v_subrev_u32_e32 v25, s93, v26
	v_subrev_u32_e32 v32, s93, v27
	v_subrev_u32_e32 v33, s93, v30
	v_cvt_f32_i32_e32 v24, v24
	v_cvt_f32_i32_e32 v25, v25
	v_cvt_f32_i32_e32 v32, v32
	v_cvt_f32_i32_e32 v33, v33
	v_mul_f32_e64 v24, s89, |v24|
	v_mul_f32_e64 v25, s89, |v25|
	v_mul_f32_e64 v32, s89, |v32|
	v_mul_f32_e64 v33, s89, |v33|
	v_exp_f32_e32 v98, v24
	v_add_co_u32_e32 v24, vcc, s21, v6
	v_exp_f32_e32 v99, v25
	v_exp_f32_e32 v100, v32
	v_exp_f32_e32 v101, v33
	v_addc_co_u32_e32 v25, vcc, 0, v7, vcc
	s_xor_b32 s94, s93, -16
	v_add_u32_e32 v40, v156, v62
	s_lshl_b32 s93, s92, 5
	s_or_b32 s92, s92, 1
	v_add_u32_e32 v26, s94, v26
	v_add_u32_e32 v27, s94, v27
	v_add_u32_e32 v177, s93, v40
	v_lshl_or_b32 v61, s92, 4, v144
	v_cvt_f32_i32_e32 v26, v26
	v_cvt_f32_i32_e32 v27, v27
	v_add_co_u32_e32 v4, vcc, s21, v4
	s_waitcnt vmcnt(4)
	ds_write_b128 v164, v[8:11]
	s_waitcnt vmcnt(3)
	ds_write_b128 v164, v[12:15] offset:9216
	v_lshlrev_b32_e32 v8, 16, v12
	v_and_b32_e32 v9, 0xffff0000, v12
	v_lshlrev_b32_e32 v10, 16, v13
	v_and_b32_e32 v11, 0xffff0000, v13
	v_pk_mul_f32 v[8:9], v[102:103], v[8:9] op_sel_hi:[0,1]
	v_pk_mul_f32 v[10:11], v[102:103], v[10:11] op_sel_hi:[0,1]
	v_cvt_pk_bf16_f32 v8, v8, v9
	v_cvt_pk_bf16_f32 v9, v10, v11
	v_lshlrev_b32_e32 v10, 16, v14
	v_and_b32_e32 v11, 0xffff0000, v14
	v_lshlrev_b32_e32 v12, 16, v15
	v_and_b32_e32 v13, 0xffff0000, v15
	v_pk_mul_f32 v[10:11], v[102:103], v[10:11] op_sel_hi:[0,1]
	v_pk_mul_f32 v[12:13], v[102:103], v[12:13] op_sel_hi:[0,1]
	v_cvt_pk_bf16_f32 v10, v10, v11
	v_cvt_pk_bf16_f32 v11, v12, v13
	ds_write_b128 v164, v[8:11] offset:18432
	s_waitcnt vmcnt(2)
	ds_write_b128 v165, v[16:19] offset:27648
	s_waitcnt vmcnt(1)
	ds_write_b128 v165, v[20:23] offset:36864
	s_waitcnt lgkmcnt(0)
	s_barrier
	v_mad_u32_u24 v16, v60, s20, v166
	ds_read_b128 v[8:11], v16 offset:9216
	ds_read_b128 v[12:15], v176
	ds_read_b128 v[16:19], v16 offset:9280
	v_or_b32_e32 v20, s88, v144
	v_mul_lo_u32 v48, v20, s20
	ds_read_b128 v[20:23], v176 offset:64
	s_waitcnt lgkmcnt(2)
	v_mfma_f32_16x16x32_bf16 v[8:11], v[8:11], v[12:15], 0
	v_mul_f32_e64 v26, s89, |v26|
	v_mul_f32_e64 v27, s89, |v27|
	v_exp_f32_e32 v93, v26
	s_waitcnt lgkmcnt(0)
	v_mfma_f32_16x16x32_bf16 v[6:9], v[16:19], v[20:23], v[8:11]
	v_exp_f32_e32 v94, v27
	v_addc_co_u32_e32 v5, vcc, 0, v5, vcc
	s_nop 0
	v_mad_u32_u24 v10, v61, s20, v166
	v_add_u32_e32 v31, s94, v31
	s_nop 2
	v_pk_mul_f32 v[8:9], v[100:101], v[8:9]
	v_pk_mul_f32 v[6:7], v[98:99], v[6:7]
	v_add_u32_e32 v30, s94, v30
	v_cvt_pk_bf16_f32 v6, v6, v7
	v_cvt_pk_bf16_f32 v7, v8, v9
	ds_write_b64 v177, v[6:7]
	ds_read_b128 v[6:9], v10 offset:9216
	global_load_dwordx4 v[240:243], v[24:25], off nt
	v_lshl_add_u64 v[214:215], v[24:25], 0, s[8:9]
	global_load_dwordx4 v[224:227], v[214:215], off nt
	s_nop 0
	global_load_dwordx4 v[244:247], v[4:5], off nt
	v_lshl_add_u64 v[214:215], v[4:5], 0, s[8:9]
	global_load_dwordx4 v[228:231], v[214:215], off nt
	ds_read_b128 v[16:19], v10 offset:9280
	v_cvt_f32_i32_e32 v31, v31
	v_cvt_f32_i32_e32 v30, v30
	s_waitcnt lgkmcnt(1)
	v_mfma_f32_16x16x32_bf16 v[4:7], v[6:9], v[12:15], 0
	v_mul_f32_e64 v31, s89, |v31|
	v_mul_f32_e64 v30, s89, |v30|
	v_exp_f32_e32 v92, v31
	v_exp_f32_e32 v95, v30
	s_waitcnt lgkmcnt(0)
	v_mfma_f32_16x16x32_bf16 v[4:7], v[16:19], v[20:23], v[4:7]
	v_add_co_u32_e32 v10, vcc, s56, v28
	s_lshl_b32 s92, s92, 5
	s_nop 0
	v_addc_co_u32_e32 v11, vcc, 0, v29, vcc
	v_add_co_u32_e32 v8, vcc, s57, v28
	s_nop 2
	v_pk_mul_f32 v[6:7], v[94:95], v[6:7]
	v_pk_mul_f32 v[4:5], v[92:93], v[4:5]
	v_add_u32_e32 v142, s92, v40
	v_cvt_pk_bf16_f32 v4, v4, v5
	v_cvt_pk_bf16_f32 v5, v6, v7
	v_addc_co_u32_e32 v9, vcc, 0, v29, vcc
	global_load_dwordx4 v[248:251], v[10:11], off nt
	v_lshl_add_u64 v[214:215], v[10:11], 0, s[12:13]
	global_load_dwordx4 v[232:235], v[214:215], off nt
	global_load_dwordx4 v[252:255], v[8:9], off nt
	v_lshl_add_u64 v[214:215], v[8:9], 0, s[12:13]
	global_load_dwordx4 v[236:239], v[214:215], off nt
	ds_write_b64 v142, v[4:5]
	v_add_u32_e32 v137, v161, v48
	s_waitcnt lgkmcnt(0)
	s_barrier
; #define LAS __attribute__((address_space(3)))
; __device__ __forceinline__ unsigned pk2(float lo, float hi) { return pg8::cvt_pk_bf16(lo, hi); }
; __device__ __forceinline__ f32x4 mfma16(bf16x8 a, bf16x8 b, f32x4 c) { return __builtin_amdgcn_mfma_f32_16x16x32_bf16(a, b, c, 0, 0, 0); }
; __device__ __forceinline__ void retention_unit(LAS unsigned char* lds, const Ptrs& P, int b, int h, int tid) {
;     ...
;         if (n < 32) {
;             f32x4 o[4]; bf16x8 bst[2], bv[2];
; #pragma unroll
;             for (int ks = 0; ks < 2; ++ks) { bst[ks] = *(const LAS bf16x8*)(St + (16 * w + fr) * S72 + 32 * ks + 8 * fq); bv[ks] = tr_frag(bufc + ROFF_V, S144 * 2, w, ks, fq, fr); }
; #pragma unroll
;             for (int it = 0; it < 4; ++it) { o[it] = (f32x4){0.f, 0.f, 0.f, 0.f};
; #pragma unroll
;                 for (int ks = 0; ks < 2; ++ks) { const bf16x8 qf = *(const LAS bf16x8*)(Qs + (16 * it + fr) * S72 + 32 * ks + 8 * fq); o[it] = mfma16(bst[ks], qf, o[it]); }
;                 o[it] = o[it] * dqv[it];
; #pragma unroll
;                 for (int ks = 0; ks < 2; ++ks) { const bf16x8 sf = *(const LAS bf16x8*)(Ss + (16 * it + fr) * S72 + 32 * ks + 8 * fq); o[it] = mfma16(bv[ks], sf, o[it]); }
;             }
; #pragma unroll
;             for (int dt = 0; dt < 4; ++dt) { st[dt] = st[dt] * dch;
; #pragma unroll
;                 for (int ks = 0; ks < 2; ++ks) { const bf16x8 kf = tr_frag(bufc + ROFF_K2, S72 * 2, dt, ks, fq, fr); st[dt] = mfma16(kf, bv[ks], st[dt]); }
;                 v2u pw; pw.x = pk2(st[dt][0], st[dt][1]); pw.y = pk2(st[dt][2], st[dt][3]);
;                 *(LAS v2u*)(St + (16 * w + fr) * S72 + 16 * dt + 4 * fq) = pw; }
; #pragma unroll
;             for (int it = 0; it < 4; ++it) { const f32x4 v = o[it]; typedef float f32x2 __attribute__((ext_vector_type(2)));
;                 *(LAS f32x2*)(part + ((16 * it + fr) * 32 + w * 4 + fq) * 2) = (f32x2){(v[0] + v[1]) + (v[2] + v[3]), (v[0] * v[0] + v[1] * v[1]) + (v[2] * v[2] + v[3] * v[3])};
;                 op[it] = v; }
	ds_read_b128 v[4:7], v137
	ds_read_b128 v[8:11], v137 offset:64
	ds_read_b128 v[12:15], v128
	v_mul_f32_e32 v16, s89, v148
	v_exp_f32_e32 v90, v16
	ds_read_b128 v[16:19], v128 offset:64
	s_waitcnt lgkmcnt(1)
	v_mfma_f32_16x16x32_bf16 v[12:15], v[4:7], v[12:15], 0
	s_lshl_b32 s87, s87, 5
	v_add3_u32 v40, v167, s87, v168
	ds_read_b64_tr_b16 v[52:53], v40 offset:27648
	ds_read_b64_tr_b16 v[54:55], v40 offset:28800
	ds_read_b64_tr_b16 v[58:59], v40 offset:38016
	s_waitcnt lgkmcnt(3)
	v_mfma_f32_16x16x32_bf16 v[12:15], v[8:11], v[16:19], v[12:15]
	ds_read_b128 v[16:19], v129
	ds_read_b64_tr_b16 v[56:57], v40 offset:36864
	v_mov_b32_e32 v91, v90
	ds_read_b128 v[20:23], v129 offset:64
	v_add_u32_e32 v132, v157, v48
	s_nop 2
	v_pk_mul_f32 v[14:15], v[90:91], v[14:15] op_sel_hi:[0,1]
	v_pk_mul_f32 v[12:13], v[90:91], v[12:13] op_sel_hi:[0,1]
	v_mul_f32_e32 v75, s89, v151
	v_exp_f32_e32 v88, v75
	s_waitcnt lgkmcnt(2)
	v_mfma_f32_16x16x32_bf16 v[12:15], v[52:55], v[16:19], v[12:15]
	s_lshl_b64 s[92:93], s[18:19], 20
	v_add_u32_e32 v133, s87, v172
	v_mov_b32_e32 v89, v88
	s_waitcnt lgkmcnt(0)
	v_mfma_f32_16x16x32_bf16 v[40:43], v[56:59], v[20:23], v[12:15]
	s_nop 2
	ds_read_b128 v[12:15], v128 offset:2304
	ds_read_b128 v[16:19], v128 offset:2368
	v_mul_f32_e32 v20, s89, v149
	v_exp_f32_e32 v78, v20
	s_waitcnt lgkmcnt(1)
	v_mfma_f32_16x16x32_bf16 v[12:15], v[4:7], v[12:15], 0
	ds_read_b128 v[20:23], v129 offset:2368
	v_mov_b32_e32 v79, v78
	s_or_b32 s92, s92, s91
	s_waitcnt lgkmcnt(1)
	v_mfma_f32_16x16x32_bf16 v[12:15], v[8:11], v[16:19], v[12:15]
	ds_read_b128 v[16:19], v129 offset:2304
	v_add_u32_e32 v134, s87, v173
	v_add_u32_e32 v135, s87, v174
	v_mul_u32_u24_e32 v179, 0x90, v60
	v_mul_u32_u24_e32 v178, 0x90, v61
	s_nop 2
	v_pk_mul_f32 v[14:15], v[78:79], v[14:15] op_sel_hi:[0,1]
	v_pk_mul_f32 v[12:13], v[78:79], v[12:13] op_sel_hi:[0,1]
	v_mov_b32_e32 v108, v90
	v_mov_b32_e32 v109, v90
	s_waitcnt lgkmcnt(0)
	v_mfma_f32_16x16x32_bf16 v[12:15], v[52:55], v[16:19], v[12:15]
	ds_read_b128 v[16:19], v128 offset:4608
	v_mov_b32_e32 v96, v88
	v_mov_b32_e32 v97, v88
	v_mfma_f32_16x16x32_bf16 v[44:47], v[56:59], v[20:23], v[12:15]
	v_mul_f32_e32 v21, s89, v150
	v_mul_f32_e32 v20, s89, v126
	v_exp_f32_e32 v86, v21
	s_nop 0
	ds_read_b128 v[12:15], v128 offset:4672
	s_waitcnt lgkmcnt(1)
	v_mfma_f32_16x16x32_bf16 v[16:19], v[4:7], v[16:19], 0
	v_exp_f32_e32 v74, v20
	v_mov_b32_e32 v87, v86
	s_mov_b32 s89, 0
	s_waitcnt lgkmcnt(0)
	v_mfma_f32_16x16x32_bf16 v[12:15], v[8:11], v[12:15], v[16:19]
	v_mul_f32_e32 v110, 0, v74
	v_mov_b32_e32 v111, v110
	v_mov_b32_e32 v112, v110
	ds_read_b128 v[16:19], v129 offset:4608
	ds_read_b64_tr_b16 v[20:21], v130 offset:18432
	ds_read_b64_tr_b16 v[22:23], v130 offset:19008
	ds_read_b128 v[48:51], v129 offset:4672
	s_nop 0
	v_pk_mul_f32 v[14:15], v[86:87], v[14:15] op_sel_hi:[0,1]
	v_pk_mul_f32 v[12:13], v[86:87], v[12:13] op_sel_hi:[0,1]
	v_mov_b32_e32 v113, v110
	v_mov_b32_e32 v76, v74
	s_waitcnt lgkmcnt(3)
	v_mfma_f32_16x16x32_bf16 v[12:15], v[52:55], v[16:19], v[12:15]
	ds_read_b64_tr_b16 v[16:17], v130 offset:23040
	ds_read_b64_tr_b16 v[18:19], v130 offset:23616
	ds_read_b128 v[104:107], v128 offset:6912
	ds_read_b128 v[114:117], v128 offset:6976
	ds_read_b128 v[118:121], v129 offset:6912
	ds_read_b128 v[138:141], v129 offset:6976
	v_mov_b32_e32 v77, v74
	s_waitcnt lgkmcnt(7)
	v_mfma_f32_16x16x32_bf16 v[20:23], v[20:23], v[52:55], v[110:113]
	v_add_u32_e32 v136, s87, v175
	s_waitcnt lgkmcnt(4)
	v_mfma_f32_16x16x32_bf16 v[16:19], v[16:19], v[56:59], v[20:23]
	v_mfma_f32_16x16x32_bf16 v[48:51], v[56:59], v[48:51], v[12:15]
	s_waitcnt lgkmcnt(3)
	v_mfma_f32_16x16x32_bf16 v[4:7], v[4:7], v[104:107], 0
	s_nop 4
	v_cvt_pk_bf16_f32 v20, v16, v17
	v_cvt_pk_bf16_f32 v21, v18, v19
	ds_write_b64 v132, v[20:21]
	ds_read_b64_tr_b16 v[20:21], v130 offset:18464
	ds_read_b64_tr_b16 v[22:23], v130 offset:19040
	ds_read_b64_tr_b16 v[12:13], v130 offset:23072
	ds_read_b64_tr_b16 v[14:15], v130 offset:23648
	s_waitcnt lgkmcnt(2)
	v_mfma_f32_16x16x32_bf16 v[20:23], v[20:23], v[52:55], v[110:113]
	s_waitcnt lgkmcnt(0)
	v_mfma_f32_16x16x32_bf16 v[12:15], v[12:15], v[56:59], v[20:23]
	v_mfma_f32_16x16x32_bf16 v[4:7], v[8:11], v[114:117], v[4:7]
	s_nop 6
	v_cvt_pk_bf16_f32 v20, v12, v13
	v_cvt_pk_bf16_f32 v21, v14, v15
	ds_write_b64 v132, v[20:21] offset:32
	ds_read_b64_tr_b16 v[20:21], v130 offset:18496
	ds_read_b64_tr_b16 v[22:23], v130 offset:19072
	ds_read_b64_tr_b16 v[104:105], v130 offset:23104
	ds_read_b64_tr_b16 v[106:107], v130 offset:23680
	s_waitcnt lgkmcnt(2)
	v_mfma_f32_16x16x32_bf16 v[8:11], v[20:23], v[52:55], v[110:113]
	v_mul_f32_e64 v6, v88, v6
	v_mul_f32_e64 v7, v88, v7
	v_pk_mul_f32 v[4:5], v[88:89], v[4:5] op_sel_hi:[0,1]
	s_waitcnt lgkmcnt(0)
	v_mfma_f32_16x16x32_bf16 v[8:11], v[104:107], v[56:59], v[8:11]
	v_mov_b32_e32 v106, v78
	v_mov_b32_e32 v107, v78
	v_mov_b32_e32 v104, v86
	v_mfma_f32_16x16x32_bf16 v[4:7], v[52:55], v[118:121], v[4:7]
	v_mov_b32_e32 v105, v86
	s_nop 2
	v_cvt_pk_bf16_f32 v20, v8, v9
	v_cvt_pk_bf16_f32 v21, v10, v11
	ds_write_b64 v132, v[20:21] offset:64
	ds_read_b64_tr_b16 v[114:115], v130 offset:18528
	ds_read_b64_tr_b16 v[116:117], v130 offset:19104
	ds_read_b64_tr_b16 v[118:119], v130 offset:23136
	ds_read_b64_tr_b16 v[120:121], v130 offset:23712
	v_mfma_f32_16x16x32_bf16 v[20:23], v[56:59], v[138:141], v[4:7]
	s_waitcnt lgkmcnt(2)
	v_mfma_f32_16x16x32_bf16 v[4:7], v[114:117], v[52:55], v[110:113]
	v_mul_f32_e32 v55, v41, v41
	v_mov_b32_e32 v54, v41
	s_waitcnt lgkmcnt(0)
; #define LAS __attribute__((address_space(3)))
; #define LBAR() do { asm volatile("s_waitcnt lgkmcnt(0)" ::: "memory"); __builtin_amdgcn_s_barrier(); asm volatile("" ::: "memory"); } while (0)
; __device__ __forceinline__ unsigned pk2(float lo, float hi) { return pg8::cvt_pk_bf16(lo, hi); }
; __device__ __forceinline__ void retention_unit(LAS unsigned char* lds, const Ptrs& P, int b, int h, int tid) {
;     ...
;         if (n >= 1) {
; #pragma unroll
;             for (int it = 0; it < 4; ++it) sgr[it] = __builtin_nontemporal_load((const v2u*)(gsl + ((size_t)(n - 1) * 64 + 16 * it) * 512));
;         }
;         LBAR();
;     ...
;         if (n >= 1) {
; #pragma unroll
;             for (int it = 0; it < 4; ++it) { const int i = 16 * it + fr; const float mean = stat[i * 2], rstd = stat[i * 2 + 1]; const v2u sg = sgr[it];
;                 const f32x4 y = (op[it] - mean) * rstd * gng4 * (f32x4){bflo(sg.x), bfhi(sg.x), bflo(sg.y), bfhi(sg.y)};
;                 v2u pw; pw.x = pk2(y[0], y[1]); pw.y = pk2(y[2], y[3]);
;                 *(v2u*)(gol + ((size_t)(n - 1) * 64 + 16 * it) * 1024) = pw; }
;     ...
;                 v2u pw; pw.x = pk2(st[dt][0], st[dt][1]); pw.y = pk2(st[dt][2], st[dt][3]);
;                 *(LAS v2u*)(St + (16 * w + fr) * S72 + 16 * dt + 4 * fq) = pw; }
; #pragma unroll
;             for (int it = 0; it < 4; ++it) { const f32x4 v = o[it]; typedef float f32x2 __attribute__((ext_vector_type(2)));
;                 *(LAS f32x2*)(part + ((16 * it + fr) * 32 + w * 4 + fq) * 2) = (f32x2){(v[0] + v[1]) + (v[2] + v[3]), (v[0] * v[0] + v[1] * v[1]) + (v[2] * v[2] + v[3] * v[3])};
;                 op[it] = v; }
	v_mfma_f32_16x16x32_bf16 v[4:7], v[118:121], v[56:59], v[4:7]
	v_mul_f32_e32 v57, v42, v42
	v_mul_f32_e32 v59, v43, v43
	v_mov_b32_e32 v56, v42
	v_mov_b32_e32 v58, v43
	v_lshl_add_u64 v[110:111], s[92:93], 0, v[64:65]
	s_nop 2
	v_cvt_pk_bf16_f32 v52, v4, v5
	v_cvt_pk_bf16_f32 v53, v6, v7
	ds_write_b64 v132, v[52:53] offset:96
	v_mul_f32_e32 v53, v40, v40
	v_mov_b32_e32 v52, v40
	v_pk_add_f32 v[52:53], v[52:53], v[54:55]
	v_pk_add_f32 v[54:55], v[56:57], v[58:59]
	v_mul_f32_e32 v57, v46, v46
	v_pk_add_f32 v[52:53], v[52:53], v[54:55]
	ds_write_b64 v133, v[52:53]
	v_mul_f32_e32 v53, v44, v44
	v_mul_f32_e32 v55, v45, v45
	v_mul_f32_e32 v59, v47, v47
	v_mov_b32_e32 v52, v44
	v_mov_b32_e32 v54, v45
	v_mov_b32_e32 v56, v46
	v_mov_b32_e32 v58, v47
	s_lshl_b64 s[92:93], s[18:19], 21
	v_pk_add_f32 v[52:53], v[52:53], v[54:55]
	v_pk_add_f32 v[54:55], v[56:57], v[58:59]
	s_or_b32 s94, s92, s90
	s_lshl_b64 s[18:19], s[18:19], 22
	v_pk_add_f32 v[52:53], v[52:53], v[54:55]
	s_add_u32 s90, s87, s90
	ds_write_b64 v134, v[52:53]
	v_mul_f32_e32 v53, v48, v48
	v_mul_f32_e32 v55, v49, v49
	v_mul_f32_e32 v57, v50, v50
	v_mul_f32_e32 v59, v51, v51
	v_mov_b32_e32 v52, v48
	v_mov_b32_e32 v54, v49
	v_mov_b32_e32 v56, v50
	v_mov_b32_e32 v58, v51
	s_addc_u32 s91, 0, 0
	v_pk_add_f32 v[52:53], v[52:53], v[54:55]
	v_pk_add_f32 v[54:55], v[56:57], v[58:59]
	s_add_u32 s18, s90, s18
	v_pk_add_f32 v[52:53], v[52:53], v[54:55]
	s_addc_u32 s19, s91, s19
	ds_write_b64 v135, v[52:53]
	v_mul_f32_e32 v53, v20, v20
	v_mul_f32_e32 v55, v21, v21
	v_mul_f32_e32 v57, v22, v22
	v_mul_f32_e32 v59, v23, v23
	v_mov_b32_e32 v52, v20
	v_mov_b32_e32 v54, v21
	v_mov_b32_e32 v56, v22
	v_mov_b32_e32 v58, v23
	v_lshl_add_u64 v[114:115], s[18:19], 0, v[68:69]
	s_add_u32 s18, s90, s92
	v_pk_add_f32 v[52:53], v[52:53], v[54:55]
	v_pk_add_f32 v[54:55], v[56:57], v[58:59]
	s_mov_b32 s95, s93
	s_addc_u32 s19, s91, s93
	v_pk_add_f32 v[52:53], v[52:53], v[54:55]
	v_lshl_add_u64 v[112:113], s[94:95], 0, v[66:67]
	v_lshl_add_u64 v[116:117], s[18:19], 0, v[70:71]
	ds_write_b64 v136, v[52:53]
	v_lshl_add_u64 v[184:185], s[26:27], 0, v[116:117]
	v_add_co_u32_e32 v186, vcc, s58, v184
	s_nop 1
	v_addc_co_u32_e32 v187, vcc, 0, v185, vcc
	v_add_co_u32_e32 v188, vcc, s59, v184
	s_nop 1
	v_addc_co_u32_e32 v189, vcc, 0, v185, vcc
	v_add_co_u32_e32 v190, vcc, s60, v184
	s_nop 1
	v_addc_co_u32_e32 v191, vcc, 0, v185, vcc
	v_add_co_u32_e32 v192, vcc, s61, v184
	s_nop 1
	v_addc_co_u32_e32 v193, vcc, 0, v185, vcc
	global_load_dwordx2 v[216:217], v[186:187], off nt
	global_load_dwordx2 v[218:219], v[188:189], off nt
	global_load_dwordx2 v[220:221], v[190:191], off nt
	global_load_dwordx2 v[222:223], v[192:193], off nt
	s_waitcnt vmcnt(0)
	s_branch .LBB0_658
.LBB0_657:
	s_or_b64 exec, exec, s[18:19]
	v_lshl_add_u32 v60, v155, 1, s90
	v_add_u32_e32 v61, v60, v179
	s_waitcnt lgkmcnt(0)
	ds_read_b128 v[56:59], v61 offset:9216
	v_add_u32_e32 v75, v60, v62
	ds_read_b128 v[184:187], v61 offset:9280
	ds_read_b128 v[188:191], v75
	ds_read_b128 v[192:195], v75 offset:64
	v_add_u32_e32 v60, v60, v178
	v_and_b32_e32 v61, 0xffff0000, v54
	v_add_u32_e32 v75, 0, v160
	v_add_u32_e32 v143, 0x21400, v75
	v_lshl_add_u64 v[120:121], s[26:27], 0, v[114:115]
	v_add3_u32 v204, s90, v82, v169
	s_waitcnt lgkmcnt(1)
	v_mfma_f32_16x16x32_bf16 v[56:59], v[56:59], v[188:191], 0
	s_add_i32 s18, s90, s87
	v_lshlrev_b32_e32 v200, 16, v122
	v_and_b32_e32 v201, 0xffff0000, v122
	s_waitcnt lgkmcnt(0)
	v_mfma_f32_16x16x32_bf16 v[56:59], v[184:187], v[192:195], v[56:59]
	v_lshlrev_b32_e32 v122, 16, v123
	v_and_b32_e32 v123, 0xffff0000, v123
	v_add3_u32 v212, s90, v162, v170
	v_mov_b32_e32 v75, v74
	v_pk_mul_f32 v[18:19], v[74:75], v[18:19]
	s_nop 2
	v_pk_mul_f32 v[58:59], v[100:101], v[58:59]
	v_pk_mul_f32 v[56:57], v[98:99], v[56:57]
	v_pk_mul_f32 v[16:17], v[76:77], v[16:17]
	v_cvt_pk_bf16_f32 v56, v56, v57
	v_cvt_pk_bf16_f32 v57, v58, v59
	ds_write_b64 v177, v[56:57]
	ds_read_b128 v[56:59], v60 offset:9216
	ds_read_b128 v[184:187], v60 offset:9280
	s_waitcnt lgkmcnt(1)
	v_mfma_f32_16x16x32_bf16 v[56:59], v[56:59], v[188:191], 0
	v_lshlrev_b32_e32 v60, 16, v54
	v_lshlrev_b32_e32 v188, 16, v55
	v_and_b32_e32 v189, 0xffff0000, v55
	s_waitcnt lgkmcnt(0)
	v_mfma_f32_16x16x32_bf16 v[54:57], v[184:187], v[192:195], v[56:59]
	v_mul_f32_e64 v14, v74, v14
	v_mul_f32_e64 v15, v75, v15
	v_pk_mul_f32 v[12:13], v[76:77], v[12:13]
	v_pk_mul_f32 v[10:11], v[74:75], v[10:11]
	v_add_co_u32_e32 v58, vcc, s66, v120
	v_pk_mul_f32 v[8:9], v[76:77], v[8:9]
	s_nop 1
	v_pk_mul_f32 v[56:57], v[94:95], v[56:57]
	v_pk_mul_f32 v[54:55], v[92:93], v[54:55]
	v_addc_co_u32_e32 v59, vcc, 0, v121, vcc
	v_cvt_pk_bf16_f32 v54, v54, v55
	v_cvt_pk_bf16_f32 v55, v56, v57
	ds_write_b64 v142, v[54:55]
	s_waitcnt lgkmcnt(0)
	s_barrier
; #define LAS __attribute__((address_space(3)))
; __device__ __forceinline__ unsigned pk2(float lo, float hi) { return pg8::cvt_pk_bf16(lo, hi); }
; __device__ __forceinline__ f32x4 mfma16(bf16x8 a, bf16x8 b, f32x4 c) { return __builtin_amdgcn_mfma_f32_16x16x32_bf16(a, b, c, 0, 0, 0); }
; __device__ __forceinline__ void retention_unit(LAS unsigned char* lds, const Ptrs& P, int b, int h, int tid) {
;     ...
;         if (n >= 1) {
; #pragma unroll
;             for (int it = 0; it < 4; ++it) { const int i = 16 * it + fr; const float mean = stat[i * 2], rstd = stat[i * 2 + 1]; const v2u sg = sgr[it];
;                 const f32x4 y = (op[it] - mean) * rstd * gng4 * (f32x4){bflo(sg.x), bfhi(sg.x), bflo(sg.y), bfhi(sg.y)};
;                 v2u pw; pw.x = pk2(y[0], y[1]); pw.y = pk2(y[2], y[3]);
;                 *(v2u*)(gol + ((size_t)(n - 1) * 64 + 16 * it) * 1024) = pw; }
;         }
;         if (n < 32) {
;             f32x4 o[4]; bf16x8 bst[2], bv[2];
; #pragma unroll
;             for (int ks = 0; ks < 2; ++ks) { bst[ks] = *(const LAS bf16x8*)(St + (16 * w + fr) * S72 + 32 * ks + 8 * fq); bv[ks] = tr_frag(bufc + ROFF_V, S144 * 2, w, ks, fq, fr); }
; #pragma unroll
;             for (int it = 0; it < 4; ++it) { o[it] = (f32x4){0.f, 0.f, 0.f, 0.f};
; #pragma unroll
;                 for (int ks = 0; ks < 2; ++ks) { const bf16x8 qf = *(const LAS bf16x8*)(Qs + (16 * it + fr) * S72 + 32 * ks + 8 * fq); o[it] = mfma16(bst[ks], qf, o[it]); }
;                 o[it] = o[it] * dqv[it];
; #pragma unroll
;                 for (int ks = 0; ks < 2; ++ks) { const bf16x8 sf = *(const LAS bf16x8*)(Ss + (16 * it + fr) * S72 + 32 * ks + 8 * fq); o[it] = mfma16(bv[ks], sf, o[it]); }
;             }
; #pragma unroll
;             for (int dt = 0; dt < 4; ++dt) { st[dt] = st[dt] * dch;
; #pragma unroll
;                 for (int ks = 0; ks < 2; ++ks) { const bf16x8 kf = tr_frag(bufc + ROFF_K2, S72 * 2, dt, ks, fq, fr); st[dt] = mfma16(kf, bv[ks], st[dt]); }
	ds_read2_b64 v[54:57], v143 offset1:16
	ds_read_b128 v[184:187], v137
	v_pk_mul_f32 v[6:7], v[74:75], v[6:7]
	v_pk_mul_f32 v[4:5], v[76:77], v[4:5]
	v_lshl_add_u64 v[110:111], v[110:111], 0, s[8:9]
	s_waitcnt lgkmcnt(1)
	v_sub_f32_e32 v41, v41, v54
	v_sub_f32_e32 v40, v40, v54
	v_sub_f32_e32 v43, v43, v54
	v_sub_f32_e32 v42, v42, v54
	v_pk_mul_f32 v[42:43], v[54:55], v[42:43] op_sel:[1,0]
	v_pk_mul_f32 v[40:41], v[54:55], v[40:41] op_sel:[1,0]
	v_pk_mul_f32 v[42:43], v[2:3], v[42:43]
	v_pk_mul_f32 v[40:41], v[0:1], v[40:41]
	v_pk_mul_f32 v[42:43], v[42:43], v[188:189]
	v_pk_mul_f32 v[40:41], v[40:41], v[60:61]
	v_sub_f32_e32 v45, v45, v56
	v_cvt_pk_bf16_f32 v40, v40, v41
	v_cvt_pk_bf16_f32 v41, v42, v43
	v_sub_f32_e32 v44, v44, v56
	global_store_dwordx2 v[58:59], v[40:41], off
	v_sub_f32_e32 v41, v47, v56
	v_sub_f32_e32 v40, v46, v56
	v_pk_mul_f32 v[40:41], v[56:57], v[40:41] op_sel:[1,0]
	v_pk_mul_f32 v[42:43], v[56:57], v[44:45] op_sel:[1,0]
	ds_read2_b64 v[54:57], v143 offset0:32 offset1:48
	v_pk_mul_f32 v[42:43], v[0:1], v[42:43]
	v_pk_mul_f32 v[40:41], v[2:3], v[40:41]
	v_lshlrev_b32_e32 v44, 16, v52
	v_and_b32_e32 v45, 0xffff0000, v52
	v_lshlrev_b32_e32 v46, 16, v53
	v_and_b32_e32 v47, 0xffff0000, v53
	v_pk_mul_f32 v[40:41], v[40:41], v[46:47]
	v_pk_mul_f32 v[42:43], v[42:43], v[44:45]
	ds_read_b128 v[188:191], v137 offset:64
	v_cvt_pk_bf16_f32 v42, v42, v43
	v_cvt_pk_bf16_f32 v43, v40, v41
	v_add_co_u32_e32 v40, vcc, s67, v120
	ds_read_b128 v[44:47], v204 offset:64
	s_nop 0
	v_addc_co_u32_e32 v41, vcc, 0, v121, vcc
	global_store_dwordx2 v[40:41], v[42:43], off
	s_waitcnt lgkmcnt(2)
	v_sub_f32_e32 v41, v49, v54
	v_sub_f32_e32 v40, v48, v54
	v_sub_f32_e32 v43, v51, v54
	v_sub_f32_e32 v42, v50, v54
	v_pk_mul_f32 v[40:41], v[54:55], v[40:41] op_sel:[1,0]
	v_pk_mul_f32 v[192:193], v[54:55], v[42:43] op_sel:[1,0]
	v_pk_mul_f32 v[196:197], v[0:1], v[40:41]
	ds_read_b128 v[40:43], v204
	s_waitcnt lgkmcnt(0)
	v_mfma_f32_16x16x32_bf16 v[40:43], v[184:187], v[40:43], 0
	v_add3_u32 v48, s18, v162, v168
	ds_read_b64_tr_b16 v[58:59], v48 offset:27648
	ds_read_b64_tr_b16 v[60:61], v48 offset:28800
	ds_read_b64_tr_b16 v[52:53], v48 offset:36864
	ds_read_b64_tr_b16 v[54:55], v48 offset:38016
	ds_read_b128 v[48:51], v129
	v_pk_mul_f32 v[192:193], v[2:3], v[192:193]
	v_mfma_f32_16x16x32_bf16 v[40:43], v[188:191], v[44:47], v[40:43]
	ds_read_b128 v[44:47], v129 offset:64
	v_pk_mul_f32 v[122:123], v[192:193], v[122:123]
	ds_read_b128 v[192:195], v129 offset:2304
	v_lshl_add_u64 v[112:113], v[112:113], 0, s[12:13]
	v_lshl_add_u64 v[114:115], v[114:115], 0, s[14:15]
	s_nop 2
	v_pk_mul_f32 v[42:43], v[108:109], v[42:43]
	v_pk_mul_f32 v[40:41], v[90:91], v[40:41]
	s_cmp_lg_u32 s89, 30
	v_lshl_add_u64 v[116:117], v[116:117], 0, s[12:13]
	s_waitcnt lgkmcnt(2)
	v_mfma_f32_16x16x32_bf16 v[40:43], v[58:61], v[48:51], v[40:43]
	ds_read_b128 v[48:51], v204 offset:2304
	s_waitcnt lgkmcnt(2)
	v_mfma_f32_16x16x32_bf16 v[40:43], v[52:55], v[44:47], v[40:43]
	ds_read_b128 v[44:47], v204 offset:2368
	s_waitcnt lgkmcnt(1)
	v_mfma_f32_16x16x32_bf16 v[48:51], v[184:187], v[48:51], 0
	s_waitcnt lgkmcnt(0)
	v_mfma_f32_16x16x32_bf16 v[44:47], v[188:191], v[44:47], v[48:51]
	s_nop 5
	ds_read_b128 v[48:51], v129 offset:2368
	s_nop 0
	v_pk_mul_f32 v[46:47], v[106:107], v[46:47]
	v_pk_mul_f32 v[44:45], v[78:79], v[44:45]
	s_nop 1
	v_mfma_f32_16x16x32_bf16 v[44:47], v[58:61], v[192:195], v[44:47]
	v_mul_f32_e64 v192, v196, v200
	v_mul_f32_e64 v193, v197, v201
	ds_read_b128 v[200:203], v129 offset:4608
	v_cvt_pk_bf16_f32 v192, v192, v193
	s_waitcnt lgkmcnt(1)
	v_mfma_f32_16x16x32_bf16 v[44:47], v[52:55], v[48:51], v[44:47]
	ds_read_b128 v[48:51], v204 offset:4608
	v_cvt_pk_bf16_f32 v193, v122, v123
	v_add_co_u32_e32 v122, vcc, s68, v120
	v_sub_f32_e32 v197, v23, v56
	s_nop 0
	v_addc_co_u32_e32 v123, vcc, 0, v121, vcc
	global_store_dwordx2 v[122:123], v[192:193], off
	ds_read_b128 v[192:195], v204 offset:4672
	s_waitcnt lgkmcnt(1)
	v_mfma_f32_16x16x32_bf16 v[48:51], v[184:187], v[48:51], 0
	v_sub_f32_e32 v123, v21, v56
	v_sub_f32_e32 v122, v20, v56
	v_sub_f32_e32 v196, v22, v56
	s_waitcnt lgkmcnt(0)
	v_mfma_f32_16x16x32_bf16 v[48:51], v[188:191], v[192:195], v[48:51]
	ds_read_b128 v[192:195], v129 offset:4672
	v_pk_mul_f32 v[196:197], v[56:57], v[196:197] op_sel:[1,0]
	v_pk_mul_f32 v[56:57], v[56:57], v[122:123] op_sel:[1,0]
	v_pk_mul_f32 v[122:123], v[2:3], v[196:197]
	v_pk_mul_f32 v[56:57], v[0:1], v[56:57]
	s_nop 2
	v_pk_mul_f32 v[50:51], v[104:105], v[50:51]
	v_pk_mul_f32 v[48:49], v[86:87], v[48:49]
	v_lshlrev_b32_e32 v196, 16, v118
	v_and_b32_e32 v197, 0xffff0000, v118
	v_mfma_f32_16x16x32_bf16 v[48:51], v[58:61], v[200:203], v[48:51]
	ds_read_b64_tr_b16 v[200:201], v212 offset:18432
	ds_read_b64_tr_b16 v[202:203], v212 offset:19008
	ds_read_b64_tr_b16 v[20:21], v212 offset:23040
	ds_read_b64_tr_b16 v[22:23], v212 offset:23616
	s_waitcnt lgkmcnt(2)
	v_mfma_f32_16x16x32_bf16 v[16:19], v[200:203], v[58:61], v[16:19]
	s_waitcnt lgkmcnt(0)
	v_mfma_f32_16x16x32_bf16 v[16:19], v[20:23], v[52:55], v[16:19]
	v_mfma_f32_16x16x32_bf16 v[48:51], v[52:55], v[192:195], v[48:51]
	ds_read_b128 v[192:195], v204 offset:6912
	ds_read_b128 v[200:203], v204 offset:6976
	ds_read_b128 v[204:207], v129 offset:6912
	ds_read_b128 v[208:211], v129 offset:6976
	s_nop 2
	v_cvt_pk_bf16_f32 v20, v16, v17
	v_cvt_pk_bf16_f32 v21, v18, v19
	ds_write_b64 v132, v[20:21]
	ds_read_b64_tr_b16 v[20:21], v212 offset:18464
	ds_read_b64_tr_b16 v[22:23], v212 offset:19040
	s_waitcnt lgkmcnt(6)
	v_mfma_f32_16x16x32_bf16 v[184:187], v[184:187], v[192:195], 0
	ds_read_b64_tr_b16 v[192:193], v212 offset:23072
	ds_read_b64_tr_b16 v[194:195], v212 offset:23648
	s_waitcnt lgkmcnt(2)
; __device__ __forceinline__ void retention_unit(LAS unsigned char* lds, const Ptrs& P, int b, int h, int tid) {
;     ...
;         if (n < 32) {
; #pragma unroll
;             for (int j2 = 0; j2 < 2; ++j2) {
;                 const int jt = (w & 1) * 2 + j2; f32x4 a4 = (f32x4){0.f, 0.f, 0.f, 0.f};
; #pragma unroll
;                 for (int ks = 0; ks < 2; ++ks) {
;                     const bf16x8 qf = *(const LAS bf16x8*)(Qs + (16 * it3 + fr) * S72 + 32 * ks + 8 * fq), kf = *(const LAS bf16x8*)(Ks + (16 * jt + fr) * S72 + 32 * ks + 8 * fq);
;                     a4 = mfma16(kf, qf, a4); }
;                 a4 = a4 * decv[j2];
;                 v2u pw; pw.x = pk2(a4[0], a4[1]); pw.y = pk2(a4[2], a4[3]);
;                 *(LAS v2u*)(Ss + (16 * it3 + fr) * S72 + 16 * jt + 4 * fq) = pw;
;             }
;         }
;         LBAR();
;         if (n >= 1) {
; #pragma unroll
;             for (int it = 0; it < 4; ++it) { const int i = 16 * it + fr; const float mean = stat[i * 2], rstd = stat[i * 2 + 1]; const v2u sg = sgr[it];
;                 const f32x4 y = (op[it] - mean) * rstd * gng4 * (f32x4){bflo(sg.x), bfhi(sg.x), bflo(sg.y), bfhi(sg.y)};
;                 v2u pw; pw.x = pk2(y[0], y[1]); pw.y = pk2(y[2], y[3]);
;                 *(v2u*)(gol + ((size_t)(n - 1) * 64 + 16 * it) * 1024) = pw; }
;         }
;         if (n < 32) {
;             f32x4 o[4]; bf16x8 bst[2], bv[2];
; #pragma unroll
;             for (int ks = 0; ks < 2; ++ks) { bst[ks] = *(const LAS bf16x8*)(St + (16 * w + fr) * S72 + 32 * ks + 8 * fq); bv[ks] = tr_frag(bufc + ROFF_V, S144 * 2, w, ks, fq, fr); }
; #pragma unroll
;             for (int it = 0; it < 4; ++it) { o[it] = (f32x4){0.f, 0.f, 0.f, 0.f};
; #pragma unroll
;                 for (int ks = 0; ks < 2; ++ks) { const bf16x8 qf = *(const LAS bf16x8*)(Qs + (16 * it + fr) * S72 + 32 * ks + 8 * fq); o[it] = mfma16(bst[ks], qf, o[it]); }
;                 o[it] = o[it] * dqv[it];
; #pragma unroll
;                 for (int ks = 0; ks < 2; ++ks) { const bf16x8 sf = *(const LAS bf16x8*)(Ss + (16 * it + fr) * S72 + 32 * ks + 8 * fq); o[it] = mfma16(bv[ks], sf, o[it]); }
;             }
; #pragma unroll
;             for (int dt = 0; dt < 4; ++dt) { st[dt] = st[dt] * dch;
; #pragma unroll
;                 for (int ks = 0; ks < 2; ++ks) { const bf16x8 kf = tr_frag(bufc + ROFF_K2, S72 * 2, dt, ks, fq, fr); st[dt] = mfma16(kf, bv[ks], st[dt]); }
	v_mfma_f32_16x16x32_bf16 v[12:15], v[20:23], v[58:61], v[12:15]
	s_waitcnt lgkmcnt(0)
	v_mfma_f32_16x16x32_bf16 v[12:15], v[192:195], v[52:55], v[12:15]
	v_mfma_f32_16x16x32_bf16 v[184:187], v[188:191], v[200:203], v[184:187]
	s_nop 6
	v_cvt_pk_bf16_f32 v20, v12, v13
	v_cvt_pk_bf16_f32 v21, v14, v15
	ds_write_b64 v132, v[20:21] offset:32
	ds_read_b64_tr_b16 v[20:21], v212 offset:18496
	ds_read_b64_tr_b16 v[22:23], v212 offset:19072
	ds_read_b64_tr_b16 v[188:189], v212 offset:23104
	ds_read_b64_tr_b16 v[190:191], v212 offset:23680
	s_waitcnt lgkmcnt(2)
	v_mfma_f32_16x16x32_bf16 v[8:11], v[20:23], v[58:61], v[8:11]
	v_mul_f32_e64 v186, v96, v186
	v_mul_f32_e64 v187, v97, v187
	v_pk_mul_f32 v[184:185], v[88:89], v[184:185]
	v_lshlrev_b32_e32 v20, 16, v119
	s_waitcnt lgkmcnt(0)
	v_mfma_f32_16x16x32_bf16 v[8:11], v[188:191], v[52:55], v[8:11]
	v_and_b32_e32 v21, 0xffff0000, v119
	v_pk_mul_f32 v[20:21], v[122:123], v[20:21]
	v_mfma_f32_16x16x32_bf16 v[184:187], v[58:61], v[204:207], v[184:187]
	s_nop 4
	v_cvt_pk_bf16_f32 v22, v8, v9
	v_cvt_pk_bf16_f32 v23, v10, v11
	ds_write_b64 v132, v[22:23] offset:64
	ds_read_b64_tr_b16 v[188:189], v212 offset:18528
	ds_read_b64_tr_b16 v[190:191], v212 offset:19104
	v_pk_mul_f32 v[22:23], v[56:57], v[196:197]
	v_cvt_pk_bf16_f32 v57, v20, v21
	v_cvt_pk_bf16_f32 v56, v22, v23
	v_mfma_f32_16x16x32_bf16 v[20:23], v[52:55], v[208:211], v[184:187]
	s_nop 2
	ds_read_b64_tr_b16 v[184:185], v212 offset:23136
	ds_read_b64_tr_b16 v[186:187], v212 offset:23712
	s_waitcnt lgkmcnt(2)
	v_mfma_f32_16x16x32_bf16 v[4:7], v[188:191], v[58:61], v[4:7]
	v_add_co_u32_e32 v58, vcc, s69, v120
	s_waitcnt lgkmcnt(0)
	v_mfma_f32_16x16x32_bf16 v[4:7], v[184:187], v[52:55], v[4:7]
	v_addc_co_u32_e32 v59, vcc, 0, v121, vcc
	global_store_dwordx2 v[58:59], v[56:57], off
	v_mul_f32_e32 v55, v41, v41
	v_mul_f32_e32 v57, v42, v42
	s_nop 3
	v_cvt_pk_bf16_f32 v52, v4, v5
	v_cvt_pk_bf16_f32 v53, v6, v7
	ds_write_b64 v132, v[52:53] offset:96
	v_mul_f32_e32 v53, v40, v40
	v_mul_f32_e32 v59, v43, v43
	v_mov_b32_e32 v52, v40
	v_mov_b32_e32 v54, v41
	v_mov_b32_e32 v56, v42
	v_mov_b32_e32 v58, v43
	v_pk_add_f32 v[52:53], v[52:53], v[54:55]
	v_pk_add_f32 v[54:55], v[56:57], v[58:59]
	v_mul_f32_e32 v57, v46, v46
	v_pk_add_f32 v[52:53], v[52:53], v[54:55]
	ds_write_b64 v133, v[52:53]
	v_mul_f32_e32 v53, v44, v44
	v_mul_f32_e32 v55, v45, v45
	v_mul_f32_e32 v59, v47, v47
	v_mov_b32_e32 v52, v44
	v_mov_b32_e32 v54, v45
	v_mov_b32_e32 v56, v46
	v_mov_b32_e32 v58, v47
	v_pk_add_f32 v[52:53], v[52:53], v[54:55]
	v_pk_add_f32 v[54:55], v[56:57], v[58:59]
	v_mul_f32_e32 v57, v50, v50
	v_pk_add_f32 v[52:53], v[52:53], v[54:55]
	ds_write_b64 v134, v[52:53]
	v_mul_f32_e32 v53, v48, v48
	v_mul_f32_e32 v55, v49, v49
	v_mul_f32_e32 v59, v51, v51
	v_mov_b32_e32 v52, v48
	v_mov_b32_e32 v54, v49
	v_mov_b32_e32 v56, v50
	v_mov_b32_e32 v58, v51
	v_pk_add_f32 v[52:53], v[52:53], v[54:55]
	v_pk_add_f32 v[54:55], v[56:57], v[58:59]
	v_mul_f32_e32 v57, v22, v22
	v_pk_add_f32 v[52:53], v[52:53], v[54:55]
	ds_write_b64 v135, v[52:53]
	v_mul_f32_e32 v53, v20, v20
	v_mul_f32_e32 v55, v21, v21
	v_mul_f32_e32 v59, v23, v23
	v_mov_b32_e32 v52, v20
	v_mov_b32_e32 v54, v21
	v_mov_b32_e32 v56, v22
	v_mov_b32_e32 v58, v23
	v_pk_add_f32 v[52:53], v[52:53], v[54:55]
	v_pk_add_f32 v[54:55], v[56:57], v[58:59]
	s_nop 0
	v_pk_add_f32 v[52:53], v[52:53], v[54:55]
	ds_write_b64 v136, v[52:53]
	s_cbranch_scc0 .LBB0_660
.LBB0_658:
	s_add_i32 s89, s89, 1
	s_bitcmp1_b32 s89, 0
	s_cselect_b32 s18, 0xb400, 0
	s_cselect_b64 s[98:99], -1, 0
	s_add_i32 s90, s18, 0
	v_add3_u32 v52, s90, v163, v72
	s_waitcnt vmcnt(16)
	v_cndmask_b32_e64 v36, v224, v240, s[98:99]
	v_cndmask_b32_e64 v37, v225, v241, s[98:99]
	v_cndmask_b32_e64 v38, v226, v242, s[98:99]
	v_cndmask_b32_e64 v39, v227, v243, s[98:99]
	v_cndmask_b32_e64 v24, v228, v244, s[98:99]
	v_cndmask_b32_e64 v25, v229, v245, s[98:99]
	v_cndmask_b32_e64 v26, v230, v246, s[98:99]
	v_cndmask_b32_e64 v27, v231, v247, s[98:99]
	v_cndmask_b32_e64 v28, v232, v248, s[98:99]
	v_cndmask_b32_e64 v29, v233, v249, s[98:99]
	v_cndmask_b32_e64 v30, v234, v250, s[98:99]
	v_cndmask_b32_e64 v31, v235, v251, s[98:99]
	v_cndmask_b32_e64 v32, v236, v252, s[98:99]
	v_cndmask_b32_e64 v33, v237, v253, s[98:99]
	v_cndmask_b32_e64 v34, v238, v254, s[98:99]
	v_cndmask_b32_e64 v35, v239, v255, s[98:99]
	ds_write_b128 v52, v[36:39]
	ds_write_b128 v52, v[24:27] offset:9216
	v_lshlrev_b32_e32 v36, 16, v24
	v_and_b32_e32 v37, 0xffff0000, v24
	v_pk_mul_f32 v[36:37], v[102:103], v[36:37]
	v_add_u32_e32 v56, 0, v159
	v_cvt_pk_bf16_f32 v24, v36, v37
	v_lshlrev_b32_e32 v36, 16, v25
	v_and_b32_e32 v37, 0xffff0000, v25
	v_pk_mul_f32 v[36:37], v[102:103], v[36:37]
	v_add_u32_e32 v139, 0x1d400, v56
	v_cvt_pk_bf16_f32 v25, v36, v37
	v_lshlrev_b32_e32 v36, 16, v26
	v_and_b32_e32 v37, 0xffff0000, v26
	v_pk_mul_f32 v[36:37], v[102:103], v[36:37]
	v_and_b32_e32 v60, 64, v131
	v_cvt_pk_bf16_f32 v26, v36, v37
	v_lshlrev_b32_e32 v36, 16, v27
	v_and_b32_e32 v37, 0xffff0000, v27
	v_pk_mul_f32 v[36:37], v[102:103], v[36:37]
	v_add_u32_e32 v60, 64, v60
	v_cvt_pk_bf16_f32 v27, v36, v37
	ds_write_b128 v52, v[24:27] offset:18432
	v_add3_u32 v24, s90, v158, v84
	ds_write_b128 v24, v[28:31] offset:27648
	ds_write_b128 v24, v[32:35] offset:36864
	v_lshl_add_u64 v[24:25], s[26:27], 0, v[116:117]
	v_lshl_add_u64 v[24:25], v[24:25], 0, s[12:13]
	v_add_co_u32_e32 v26, vcc, s58, v24
	v_xor_b32_e32 v61, 1, v131
	s_nop 0
	v_addc_co_u32_e32 v27, vcc, 0, v25, vcc
	v_add_co_u32_e32 v28, vcc, s59, v24
	s_nop 1
	v_addc_co_u32_e32 v29, vcc, 0, v25, vcc
	v_add_co_u32_e32 v30, vcc, s60, v24
	s_nop 1
	v_addc_co_u32_e32 v31, vcc, 0, v25, vcc
	v_add_co_u32_e32 v24, vcc, s61, v24
	s_nop 1
	v_addc_co_u32_e32 v25, vcc, 0, v25, vcc
	s_waitcnt vmcnt(8)
	v_mov_b32_e32 v54, v216
	v_mov_b32_e32 v55, v217
	v_mov_b32_e32 v52, v218
	v_mov_b32_e32 v53, v219
	v_mov_b32_e32 v122, v220
	v_mov_b32_e32 v123, v221
	v_mov_b32_e32 v118, v222
	v_mov_b32_e32 v119, v223
	global_load_dwordx2 v[216:217], v[26:27], off nt
	global_load_dwordx2 v[218:219], v[28:29], off nt
	global_load_dwordx2 v[220:221], v[30:31], off nt
	global_load_dwordx2 v[222:223], v[24:25], off nt
	v_lshl_add_u64 v[24:25], s[26:27], 0, v[110:111]
	v_lshl_add_u64 v[24:25], v[24:25], 0, s[8:9]
	v_add_co_u32_e32 v26, vcc, s62, v24
	s_nop 1
	v_addc_co_u32_e32 v27, vcc, 0, v25, vcc
	v_add_co_u32_e32 v24, vcc, s63, v24
	s_nop 1
	v_addc_co_u32_e32 v25, vcc, 0, v25, vcc
	v_lshl_add_u64 v[28:29], s[26:27], 0, v[112:113]
	v_lshl_add_u64 v[28:29], v[28:29], 0, s[12:13]
	v_add_co_u32_e32 v30, vcc, s64, v28
	s_nop 1
	v_addc_co_u32_e32 v31, vcc, 0, v29, vcc
	v_add_co_u32_e32 v32, vcc, s65, v28
	s_nop 1
	v_addc_co_u32_e32 v33, vcc, 0, v29, vcc
	s_waitcnt lgkmcnt(0)
	s_barrier
	s_bitcmp1_b32 s89, 0
	s_cbranch_scc1 .Lret_ld1
	global_load_dwordx4 v[224:227], v[26:27], off nt
	global_load_dwordx4 v[228:231], v[24:25], off nt
	global_load_dwordx4 v[232:235], v[30:31], off nt
	global_load_dwordx4 v[236:239], v[32:33], off nt
	s_branch .Lret_ldj
; #define LAS __attribute__((address_space(3)))
; #define LBAR() do { asm volatile("s_waitcnt lgkmcnt(0)" ::: "memory"); __builtin_amdgcn_s_barrier(); asm volatile("" ::: "memory"); } while (0)
; __device__ __forceinline__ unsigned pk2(float lo, float hi) { return pg8::cvt_pk_bf16(lo, hi); }
; __device__ __forceinline__ void retention_unit(LAS unsigned char* lds, const Ptrs& P, int b, int h, int tid) {
;     ...
;         if (n < 32) {
;             *(LAS v4u*)(Qs + lrow * S72 + lseg * 8) = rq; *(LAS v4u*)(Ks + lrow * S72 + lseg * 8) = rk;
;             v4u k2;
; #pragma unroll
;             for (int t = 0; t < 4; ++t) k2[t] = pk2(bflo(rk[t]) * dkey, bfhi(rk[t]) * dkey);
;             *(LAS v4u*)(K2s + lrow * S72 + lseg * 8) = k2;
;             *(LAS v4u*)(Vs + vrow0 * S144 + vseg * 8) = rv0; *(LAS v4u*)(Vs + (vrow0 + 32) * S144 + vseg * 8) = rv1;
;         }
;         if (n >= 1) {
; #pragma unroll
;             for (int it = 0; it < 4; ++it) sgr[it] = __builtin_nontemporal_load((const v2u*)(gsl + ((size_t)(n - 1) * 64 + 16 * it) * 512));
;         }
;         LBAR();
;         if (n + 1 < 32) { const size_t o4 = (size_t)(n + 1) * 64;
;             rq = __builtin_nontemporal_load((const v4u*)(gq + o4 * 256)); rk = __builtin_nontemporal_load((const v4u*)(gk + o4 * 256)); rv0 = __builtin_nontemporal_load((const v4u*)(gv + o4 * 512)); rv1 = __builtin_nontemporal_load((const v4u*)(gv + (o4 + 32) * 512)); }
;         if (n >= 1) {
;             const int row = tid >> 3, sub = tid & 7;
;             const f32x4 pa = *(const LAS f32x4*)(part + (row * 32 + sub * 4) * 2), pb = *(const LAS f32x4*)(part + (row * 32 + sub * 4) * 2 + 4);
;             float s1 = (pa[0] + pa[2]) + (pb[0] + pb[2]), s2 = (pa[1] + pa[3]) + (pb[1] + pb[3]);
; #pragma unroll
;             for (int x = 1; x < 8; x <<= 1) { s1 += __shfl_xor(s1, x); s2 += __shfl_xor(s2, x); }
;             if (sub == 0) { const float mean = s1 * (1.f / 128.f); float var = s2 * (1.f / 128.f) - mean * mean; var = var < 0.f ? 0.f : var;
;                 stat[row * 2] = mean; stat[row * 2 + 1] = __builtin_amdgcn_rsqf(var + 1e-5f); }
;         }
.Lret_ld1:
	global_load_dwordx4 v[240:243], v[26:27], off nt
	global_load_dwordx4 v[244:247], v[24:25], off nt
	global_load_dwordx4 v[248:251], v[30:31], off nt
	global_load_dwordx4 v[252:255], v[32:33], off nt
.Lret_ldj:
	ds_read_b128 v[56:59], v139
	ds_read_b128 v[184:187], v139 offset:16
	v_cmp_lt_i32_e32 vcc, v61, v60
	s_waitcnt lgkmcnt(1)
	v_pk_add_f32 v[56:57], v[56:57], v[58:59]
	v_cndmask_b32_e32 v61, v131, v61, vcc
	s_waitcnt lgkmcnt(0)
	v_pk_add_f32 v[58:59], v[184:185], v[186:187]
	v_lshlrev_b32_e32 v138, 2, v61
	v_pk_add_f32 v[56:57], v[56:57], v[58:59]
	ds_bpermute_b32 v58, v138, v56
	ds_bpermute_b32 v59, v138, v57
	v_xor_b32_e32 v61, 2, v131
	v_cmp_lt_i32_e32 vcc, v61, v60
	s_waitcnt lgkmcnt(0)
	v_pk_add_f32 v[56:57], v[56:57], v[58:59]
	v_cndmask_b32_e32 v61, v131, v61, vcc
	v_lshlrev_b32_e32 v140, 2, v61
	ds_bpermute_b32 v58, v140, v56
	ds_bpermute_b32 v59, v140, v57
	s_waitcnt lgkmcnt(0)
	v_pk_add_f32 v[56:57], v[56:57], v[58:59]
	v_xor_b32_e32 v58, 4, v131
	v_cmp_lt_i32_e32 vcc, v58, v60
	s_nop 1
	v_cndmask_b32_e32 v58, v131, v58, vcc
	v_lshlrev_b32_e32 v141, 2, v58
	ds_bpermute_b32 v58, v141, v56
	ds_bpermute_b32 v59, v141, v57
	s_and_saveexec_b64 s[18:19], s[0:1]
	s_cbranch_execz .LBB0_657
	s_waitcnt lgkmcnt(0)
	v_pk_add_f32 v[56:57], v[56:57], v[58:59]
	v_add_u32_e32 v58, 0, v198
	v_pk_mul_f32 v[56:57], v[56:57], s[6:7] op_sel_hi:[1,0]
	v_add_u32_e32 v58, 0x21400, v58
	v_fma_f32 v57, -v56, v56, v57
	v_cmp_ngt_f32_e32 vcc, 0, v57
	s_nop 1
	v_cndmask_b32_e32 v57, 0, v57, vcc
	v_add_f32_e32 v57, 0x3727c5ac, v57
	v_rsq_f32_e32 v57, v57
	ds_write2_b32 v58, v56, v57 offset1:1
	s_branch .LBB0_657
.LBB0_660:
	s_waitcnt vmcnt(16)
	v_mov_b32_e32 v36, v240
	v_mov_b32_e32 v37, v241
	v_mov_b32_e32 v38, v242
	v_mov_b32_e32 v39, v243
	v_mov_b32_e32 v24, v244
	v_mov_b32_e32 v25, v245
	v_mov_b32_e32 v26, v246
	v_mov_b32_e32 v27, v247
	v_mov_b32_e32 v28, v248
	v_mov_b32_e32 v29, v249
	v_mov_b32_e32 v30, v250
	v_mov_b32_e32 v31, v251
	v_mov_b32_e32 v32, v252
	v_mov_b32_e32 v33, v253
	v_mov_b32_e32 v34, v254
	v_mov_b32_e32 v35, v255
	v_mov_b32_e32 v53, s17
	v_or_b32_e32 v52, s16, v144
	v_lshlrev_b64 v[54:55], 10, v[52:53]
	v_lshl_add_u64 v[54:55], s[54:55], 0, v[54:55]
	s_lshl_b32 s4, s4, 1
	v_lshl_add_u64 v[54:55], v[54:55], 0, s[4:5]
	s_lshl_b32 s16, s88, 1
	s_mov_b32 s17, s5
	v_lshl_add_u64 v[54:55], v[54:55], 0, s[16:17]
	v_lshlrev_b32_e32 v62, 1, v146
	v_lshl_add_u64 v[54:55], v[54:55], 0, v[62:63]
	v_add_co_u32_e32 v56, vcc, s70, v54
	s_nop 1
	v_addc_co_u32_e32 v57, vcc, 0, v55, vcc
	v_add_co_u32_e32 v58, vcc, s71, v54
	s_nop 1
	v_addc_co_u32_e32 v59, vcc, 0, v55, vcc
	v_add_co_u32_e32 v112, vcc, s72, v54
	s_nop 1
	v_addc_co_u32_e32 v113, vcc, 0, v55, vcc
	v_add_co_u32_e32 v114, vcc, s73, v54
	s_nop 1
	v_addc_co_u32_e32 v115, vcc, 0, v55, vcc
	global_load_dwordx2 v[110:111], v[56:57], off nt
	global_load_dwordx2 v[60:61], v[58:59], off nt
	s_nop 0
	global_load_dwordx2 v[58:59], v[112:113], off nt
	global_load_dwordx2 v[56:57], v[114:115], off nt
	s_waitcnt vmcnt(11)
	ds_write_b128 v164, v[36:39] offset:46080
	s_waitcnt vmcnt(10)
	ds_write_b128 v164, v[24:27] offset:55296
	v_lshlrev_b32_e32 v36, 16, v24
	v_and_b32_e32 v37, 0xffff0000, v24
	v_pk_mul_f32 v[36:37], v[102:103], v[36:37]
	s_nop 0
	v_cvt_pk_bf16_f32 v24, v36, v37
	v_lshlrev_b32_e32 v36, 16, v25
	v_and_b32_e32 v37, 0xffff0000, v25
	v_pk_mul_f32 v[36:37], v[102:103], v[36:37]
	s_nop 0
	v_cvt_pk_bf16_f32 v25, v36, v37
	v_lshlrev_b32_e32 v36, 16, v26
	v_and_b32_e32 v37, 0xffff0000, v26
	v_pk_mul_f32 v[36:37], v[102:103], v[36:37]
	s_nop 0
	v_cvt_pk_bf16_f32 v26, v36, v37
	v_lshlrev_b32_e32 v36, 16, v27
	v_and_b32_e32 v37, 0xffff0000, v27
	v_pk_mul_f32 v[36:37], v[102:103], v[36:37]
	s_nop 0
	v_cvt_pk_bf16_f32 v27, v36, v37
	ds_write_b128 v164, v[24:27] offset:64512
	s_waitcnt vmcnt(9)
	ds_write_b128 v81, v[28:31]
	s_waitcnt vmcnt(8)
	ds_write_b128 v81, v[32:35] offset:9216
	s_waitcnt lgkmcnt(0)
	s_barrier
	ds_read_b128 v[24:27], v139
	ds_read_b128 v[28:31], v139 offset:16
	s_waitcnt lgkmcnt(1)
	v_pk_add_f32 v[24:25], v[24:25], v[26:27]
	s_waitcnt lgkmcnt(0)
	v_pk_add_f32 v[26:27], v[28:29], v[30:31]
	v_add_u32_e32 v28, 0, v198
	v_pk_add_f32 v[24:25], v[24:25], v[26:27]
	ds_bpermute_b32 v26, v138, v24
	ds_bpermute_b32 v27, v138, v25
	v_add_u32_e32 v102, 0x21400, v28
	s_waitcnt lgkmcnt(0)
	v_pk_add_f32 v[24:25], v[24:25], v[26:27]
	ds_bpermute_b32 v26, v140, v24
	ds_bpermute_b32 v27, v140, v25
	s_waitcnt lgkmcnt(0)
	v_pk_add_f32 v[24:25], v[24:25], v[26:27]
	ds_bpermute_b32 v26, v141, v24
	ds_bpermute_b32 v27, v141, v25
	s_and_saveexec_b64 s[18:19], s[0:1]
	s_cbranch_execz .LBB0_662
	s_waitcnt lgkmcnt(0)
	v_pk_add_f32 v[24:25], v[24:25], v[26:27]
	s_nop 0
	v_pk_mul_f32 v[24:25], v[24:25], s[6:7] op_sel_hi:[1,0]
	s_nop 0
	v_fma_f32 v25, -v24, v24, v25
	v_cmp_ngt_f32_e32 vcc, 0, v25
	s_nop 1
	v_cndmask_b32_e32 v25, 0, v25, vcc
	v_add_f32_e32 v25, 0x3727c5ac, v25
	v_rsq_f32_e32 v25, v25
	ds_write2_b32 v102, v24, v25 offset1:1

; __global__ void __launch_bounds__(NTHREADS, 2) mk_fwd(Args args) {
	.amdhsa_kernel _Z6mk_fwd4Args
		.amdhsa_group_segment_fixed_size 0
		.amdhsa_private_segment_fixed_size 0
		.amdhsa_kernarg_size 408
		.amdhsa_user_sgpr_count 2
		.amdhsa_user_sgpr_dispatch_ptr 0
		.amdhsa_user_sgpr_queue_ptr 0
		.amdhsa_user_sgpr_kernarg_segment_ptr 1
		.amdhsa_user_sgpr_dispatch_id 0
		.amdhsa_user_sgpr_kernarg_preload_length 0
		.amdhsa_user_sgpr_kernarg_preload_offset 0
		.amdhsa_user_sgpr_private_segment_size 0
		.amdhsa_uses_dynamic_stack 0
		.amdhsa_enable_private_segment 0
		.amdhsa_system_sgpr_workgroup_id_x 1
		.amdhsa_system_sgpr_workgroup_id_y 0
		.amdhsa_system_sgpr_workgroup_id_z 0
		.amdhsa_system_sgpr_workgroup_info 0
		.amdhsa_system_vgpr_workitem_id 2
		.amdhsa_next_free_vgpr 256
		.amdhsa_next_free_sgpr 102
		.amdhsa_accum_offset 256
		.amdhsa_reserve_vcc 1
		.amdhsa_float_round_mode_32 0
		.amdhsa_float_round_mode_16_64 0
		.amdhsa_float_denorm_mode_32 3
		.amdhsa_float_denorm_mode_16_64 3
		.amdhsa_dx10_clamp 1
		.amdhsa_ieee_mode 1
		.amdhsa_fp16_overflow 0
		.amdhsa_tg_split 0
		.amdhsa_exception_fp_ieee_invalid_op 0
		.amdhsa_exception_fp_denorm_src 0
		.amdhsa_exception_fp_ieee_div_zero 0
		.amdhsa_exception_fp_ieee_overflow 0
		.amdhsa_exception_fp_ieee_underflow 0
		.amdhsa_exception_fp_ieee_inexact 0
		.amdhsa_exception_int_div_zero 0
	.end_amdhsa_kernel

; __global__ void __launch_bounds__(NTHREADS, 2) mk_fwd(Args args) {
amdhsa.kernels:
  - .agpr_count:     0
    .args:
      - .offset:         0
        .size:           152
        .value_kind:     by_value
      - .offset:         152
        .size:           4
        .value_kind:     hidden_block_count_x
      - .offset:         156
        .size:           4
        .value_kind:     hidden_block_count_y
      - .offset:         160
        .size:           4
        .value_kind:     hidden_block_count_z
      - .offset:         164
        .size:           2
        .value_kind:     hidden_group_size_x
      - .offset:         166
        .size:           2
        .value_kind:     hidden_group_size_y
      - .offset:         168
        .size:           2
        .value_kind:     hidden_group_size_z
      - .offset:         170
        .size:           2
        .value_kind:     hidden_remainder_x
      - .offset:         172
        .size:           2
        .value_kind:     hidden_remainder_y
      - .offset:         174
        .size:           2
        .value_kind:     hidden_remainder_z
      - .offset:         192
        .size:           8
        .value_kind:     hidden_global_offset_x
      - .offset:         200
        .size:           8
        .value_kind:     hidden_global_offset_y
      - .offset:         208
        .size:           8
        .value_kind:     hidden_global_offset_z
      - .offset:         216
        .size:           2
        .value_kind:     hidden_grid_dims
      - .offset:         240
        .size:           8
        .value_kind:     hidden_multigrid_sync_arg
      - .offset:         272
        .size:           4
        .value_kind:     hidden_dynamic_lds_size
    .group_segment_fixed_size: 0
    .kernarg_segment_align: 8
    .kernarg_segment_size: 408
    .language:       OpenCL C
    .language_version:
      - 2
      - 0
    .max_flat_workgroup_size: 512
    .name:           _Z6mk_fwd4Args
    .private_segment_fixed_size: 0
    .sgpr_count:     108
    .sgpr_spill_count: 2
    .symbol:         _Z6mk_fwd4Args.kd
    .uniform_work_group_size: 1
    .uses_dynamic_stack: false
    .vgpr_count:     256
    .vgpr_spill_count: 0
    .wavefront_size: 64
